# attention second-half tile: exp/row-sum VALU moved from the post-MFMA dump into the QK^T MFMA gaps (2 per gap, same add order, in-place exps, acc in free v240)
# speedup vs baseline: 1.0019x; 1.0019x over previous
.LBB0_565:
	v_cndmask_b32_e64 v153, v148, v209, s[6:7]
	v_mul_f32_e32 v144, 0xbdd53b94, v153
	v_fmamk_f32 v80, v80, 0x3dd53b94, v144
	v_fmamk_f32 v81, v81, 0x3dd53b94, v144
	v_fmamk_f32 v82, v82, 0x3dd53b94, v144
	v_fmamk_f32 v83, v83, 0x3dd53b94, v144
	v_fmamk_f32 v84, v84, 0x3dd53b94, v144
	v_fmamk_f32 v85, v85, 0x3dd53b94, v144
	v_fmamk_f32 v86, v86, 0x3dd53b94, v144
	v_fmamk_f32 v87, v87, 0x3dd53b94, v144
	v_fmamk_f32 v88, v88, 0x3dd53b94, v144
	v_fmamk_f32 v89, v89, 0x3dd53b94, v144
	v_fmamk_f32 v90, v90, 0x3dd53b94, v144
	v_fmamk_f32 v91, v91, 0x3dd53b94, v144
	v_fmamk_f32 v92, v92, 0x3dd53b94, v144
	v_fmamk_f32 v93, v93, 0x3dd53b94, v144
	v_fmamk_f32 v94, v94, 0x3dd53b94, v144
	v_fmamk_f32 v95, v95, 0x3dd53b94, v144
	v_fmamk_f32 v218, v68, 0x3dd53b94, v144
	v_fmamk_f32 v148, v71, 0x3dd53b94, v144
	v_fmamk_f32 v149, v72, 0x3dd53b94, v144
	v_fmamk_f32 v219, v77, 0x3dd53b94, v144
	v_fmamk_f32 v155, v64, 0x3dd53b94, v144
	v_fmamk_f32 v209, v65, 0x3dd53b94, v144
	v_fmamk_f32 v216, v66, 0x3dd53b94, v144
	v_fmamk_f32 v217, v67, 0x3dd53b94, v144
	v_fmamk_f32 v146, v69, 0x3dd53b94, v144
	v_fmamk_f32 v147, v70, 0x3dd53b94, v144
	v_fmamk_f32 v150, v73, 0x3dd53b94, v144
	v_fmamk_f32 v151, v74, 0x3dd53b94, v144
	v_fmamk_f32 v154, v75, 0x3dd53b94, v144
	v_fmamk_f32 v145, v76, 0x3dd53b94, v144
	v_exp_f32_e32 v141, v80
	v_exp_f32_e32 v143, v81
	v_exp_f32_e32 v139, v82
	v_exp_f32_e32 v142, v83
	v_exp_f32_e32 v138, v84
	v_exp_f32_e32 v140, v85
	v_exp_f32_e32 v136, v86
	v_exp_f32_e32 v137, v87
	v_exp_f32_e32 v133, v88
	v_exp_f32_e32 v135, v89
	v_exp_f32_e32 v132, v90
	v_exp_f32_e32 v134, v91
	v_exp_f32_e32 v129, v92
	v_exp_f32_e32 v131, v93
	v_exp_f32_e32 v128, v94
	v_exp_f32_e32 v130, v95
	v_fmamk_f32 v220, v78, 0x3dd53b94, v144
	v_fmac_f32_e32 v144, 0x3dd53b94, v79
	s_waitcnt lgkmcnt(0)
	s_barrier
	ds_read_b128 v[64:67], v189 offset:32768
	ds_read_b128 v[68:71], v189 offset:40960
	ds_read_b128 v[222:225], v190 offset:32768
	ds_read_b128 v[226:229], v190 offset:40960
	v_exp_f32_e32 v155, v155
	v_exp_f32_e32 v209, v209
	s_waitcnt lgkmcnt(3)
	v_mfma_f32_32x32x16_bf16 v[80:95], v[64:67], v[120:123], 0
	v_exp_f32_e32 v216, v216
	v_exp_f32_e32 v217, v217
	s_waitcnt lgkmcnt(2)
	v_mfma_f32_32x32x16_bf16 v[64:79], v[68:71], v[120:123], 0
	v_add_f32_e32 v240, 0, v141
	v_add_f32_e32 v240, v143, v240
	s_waitcnt lgkmcnt(0)
	v_mfma_f32_32x32x16_bf16 v[64:79], v[226:229], v[124:127], v[64:79]
	v_add_f32_e32 v240, v139, v240
	v_add_f32_e32 v240, v142, v240
	v_mfma_f32_32x32x16_bf16 v[80:95], v[222:225], v[124:127], v[80:95]
	v_exp_f32_e32 v146, v146
	v_add_f32_e32 v240, v138, v240
	ds_read_b128 v[222:225], v191 offset:32768
	ds_read_b128 v[226:229], v191 offset:40960
	s_waitcnt lgkmcnt(0)
	v_mfma_f32_32x32x16_bf16 v[64:79], v[226:229], v[116:119], v[64:79]
	v_add_f32_e32 v240, v140, v240
	v_exp_f32_e32 v147, v147
	v_mfma_f32_32x32x16_bf16 v[80:95], v[222:225], v[116:119], v[80:95]
	v_add_f32_e32 v240, v136, v240
	v_add_f32_e32 v240, v137, v240
	ds_read_b128 v[222:225], v192 offset:32768
	ds_read_b128 v[226:229], v192 offset:40960
	s_waitcnt lgkmcnt(0)
	v_mfma_f32_32x32x16_bf16 v[64:79], v[226:229], v[112:115], v[64:79]
	v_exp_f32_e32 v154, v154
	v_add_f32_e32 v240, v133, v240
	v_mfma_f32_32x32x16_bf16 v[80:95], v[222:225], v[112:115], v[80:95]
	v_add_f32_e32 v240, v135, v240
	v_exp_f32_e32 v145, v145
	ds_read_b128 v[222:225], v193 offset:32768
	ds_read_b128 v[226:229], v193 offset:40960
	s_waitcnt lgkmcnt(0)
	v_mfma_f32_32x32x16_bf16 v[64:79], v[226:229], v[108:111], v[64:79]
	v_add_f32_e32 v240, v132, v240
	v_add_f32_e32 v240, v134, v240
	v_mfma_f32_32x32x16_bf16 v[80:95], v[222:225], v[108:111], v[80:95]
	v_exp_f32_e32 v144, v144
	v_add_f32_e32 v240, v129, v240
	ds_read_b128 v[222:225], v194 offset:32768
	ds_read_b128 v[226:229], v194 offset:40960
	s_waitcnt lgkmcnt(0)
	v_mfma_f32_32x32x16_bf16 v[64:79], v[226:229], v[104:107], v[64:79]
	v_add_f32_e32 v240, v131, v240
	v_exp_f32_e32 v218, v218
	v_mfma_f32_32x32x16_bf16 v[80:95], v[222:225], v[104:107], v[80:95]
	v_add_f32_e32 v240, v128, v240
	v_add_f32_e32 v240, v130, v240
	ds_read_b128 v[222:225], v195 offset:32768
	ds_read_b128 v[226:229], v195 offset:40960
	s_waitcnt lgkmcnt(0)
	v_mfma_f32_32x32x16_bf16 v[64:79], v[226:229], v[100:103], v[64:79]
	v_exp_f32_e32 v148, v148
	v_add_f32_e32 v240, v155, v240
	v_mfma_f32_32x32x16_bf16 v[80:95], v[222:225], v[100:103], v[80:95]
	v_add_f32_e32 v240, v209, v240
	v_exp_f32_e32 v149, v149
	ds_read_b128 v[222:225], v196 offset:32768
	ds_read_b128 v[226:229], v196 offset:40960
	s_waitcnt lgkmcnt(0)
	v_mfma_f32_32x32x16_bf16 v[64:79], v[226:229], v[96:99], v[64:79]
	v_add_f32_e32 v240, v216, v240
	v_add_f32_e32 v240, v217, v240
	v_mfma_f32_32x32x16_bf16 v[80:95], v[222:225], v[96:99], v[80:95]
	v_exp_f32_e32 v150, v150
	v_add_f32_e32 v240, v218, v240
	ds_read_b128 v[222:225], v199
	ds_read_b128 v[226:229], v199 offset:4096
	ds_read_b128 v[230:233], v197
	s_waitcnt lgkmcnt(0)
	v_mfma_f32_32x32x16_bf16 v[64:79], v[226:229], v[230:233], v[64:79]
	v_add_f32_e32 v240, v146, v240
	v_exp_f32_e32 v151, v151
	v_mfma_f32_32x32x16_bf16 v[80:95], v[222:225], v[230:233], v[80:95]
	v_add_f32_e32 v240, v147, v240
	v_add_f32_e32 v240, v148, v240
	ds_read_b128 v[222:225], v201
	ds_read_b128 v[226:229], v201 offset:4096
	ds_read_b128 v[230:233], v184
	s_waitcnt lgkmcnt(0)
	v_mfma_f32_32x32x16_bf16 v[64:79], v[226:229], v[230:233], v[64:79]
	v_exp_f32_e32 v219, v219
	v_add_f32_e32 v240, v149, v240
	v_mfma_f32_32x32x16_bf16 v[80:95], v[222:225], v[230:233], v[80:95]
	v_add_f32_e32 v240, v150, v240
	v_exp_f32_e32 v220, v220
	ds_read_b128 v[222:225], v203
	ds_read_b128 v[226:229], v203 offset:4096
	ds_read_b128 v[230:233], v183
	s_waitcnt lgkmcnt(0)
	v_mfma_f32_32x32x16_bf16 v[64:79], v[226:229], v[230:233], v[64:79]
	v_add_f32_e32 v240, v151, v240
	v_add_f32_e32 v240, v154, v240
	v_mfma_f32_32x32x16_bf16 v[80:95], v[222:225], v[230:233], v[80:95]
	v_add_f32_e32 v240, v145, v240
	v_add_f32_e32 v240, v219, v240
	ds_read_b128 v[222:225], v205
	ds_read_b128 v[226:229], v205 offset:4096
	ds_read_b128 v[230:233], v182
	s_waitcnt lgkmcnt(0)
	v_mfma_f32_32x32x16_bf16 v[64:79], v[226:229], v[230:233], v[64:79]
	v_add_f32_e32 v240, v220, v240
	v_add_f32_e32 v240, v144, v240
	v_mfma_f32_32x32x16_bf16 v[80:95], v[222:225], v[230:233], v[80:95]
	v_cvt_pk_bf16_f32 v226, v218, v146
	v_cvt_pk_bf16_f32 v227, v147, v148
	v_cvt_pk_bf16_f32 v228, v149, v150
	v_cvt_pk_bf16_f32 v229, v151, v154
	v_cvt_pk_bf16_f32 v230, v145, v219
	v_cvt_pk_bf16_f32 v231, v220, v144
	v_mov_b32_e32 v218, v240
	v_mov_b32_e32 v219, v240
	v_cvt_pk_bf16_f32 v148, v141, v143
	v_cvt_pk_bf16_f32 v149, v139, v142
	v_cvt_pk_bf16_f32 v150, v138, v140
	v_cvt_pk_bf16_f32 v151, v136, v137
	v_permlane32_swap_b32_e32 v218, v219
	v_permlane32_swap_b32_e32 v148, v150
	v_permlane32_swap_b32_e32 v149, v151
	v_cvt_pk_bf16_f32 v220, v133, v135
	v_cvt_pk_bf16_f32 v221, v132, v134
	v_cvt_pk_bf16_f32 v222, v129, v131
	v_cvt_pk_bf16_f32 v223, v128, v130
	v_cvt_pk_bf16_f32 v224, v155, v209
	v_cvt_pk_bf16_f32 v225, v216, v217
	s_nop 0
	v_permlane32_swap_b32_e32 v220, v222
	v_permlane32_swap_b32_e32 v221, v223
	v_permlane32_swap_b32_e32 v224, v226
	v_permlane32_swap_b32_e32 v225, v227
	v_permlane32_swap_b32_e32 v228, v230
	v_permlane32_swap_b32_e32 v229, v231
	s_mov_b32 s0, 0x34ec0000
	v_add_co_u32_e32 v132, vcc, s0, v172
	s_mov_b32 s0, 0x34ee0000
	s_nop 0
	v_addc_co_u32_e32 v133, vcc, 0, v173, vcc
	v_add_co_u32_e32 v136, vcc, s0, v172
	s_mov_b32 s0, 0x1ea06000
	s_nop 0
	v_addc_co_u32_e32 v137, vcc, 0, v173, vcc
	global_load_dwordx4 v[128:131], v[132:133], off offset:256
	s_nop 0
	global_load_dwordx4 v[132:135], v[132:133], off
	s_nop 0
	global_load_dwordx4 v[140:143], v[136:137], off offset:256
	s_nop 0
	global_load_dwordx4 v[136:139], v[136:137], off
	v_add_co_u32_e32 v144, vcc, s0, v174
	s_nop 1
	v_addc_co_u32_e32 v145, vcc, 0, v175, vcc
	global_load_dwordx4 v[144:147], v[144:145], off
	ds_read_b64_tr_b16 v[172:173], v180 offset:0
	ds_read_b64_tr_b16 v[174:175], v180 offset:0x800
	ds_read_b64_tr_b16 v[232:233], v180 offset:0x1000
	ds_read_b64_tr_b16 v[234:235], v180 offset:0x1800
	ds_read_b64_tr_b16 v[236:237], v180 offset:0x2000
	ds_read_b64_tr_b16 v[238:239], v180 offset:0x2800
	ds_read_b64_tr_b16 v[248:249], v180 offset:0x3000
	ds_read_b64_tr_b16 v[250:251], v180 offset:0x3800
	s_nop 0
	s_waitcnt lgkmcnt(6)
	v_mfma_f32_32x32x16_bf16 v[0:15], v[148:151], v[172:175], v[0:15]
	ds_read_b64_tr_b16 v[172:173], v180 offset:0x200
	ds_read_b64_tr_b16 v[174:175], v180 offset:0xa00
	s_waitcnt lgkmcnt(6)
	v_mfma_f32_32x32x16_bf16 v[0:15], v[220:223], v[232:235], v[0:15]
	ds_read_b64_tr_b16 v[232:233], v180 offset:0x1200
	ds_read_b64_tr_b16 v[234:235], v180 offset:0x1a00
	s_waitcnt lgkmcnt(6)
	v_mfma_f32_32x32x16_bf16 v[0:15], v[224:227], v[236:239], v[0:15]
	ds_read_b64_tr_b16 v[236:237], v180 offset:0x2200
	ds_read_b64_tr_b16 v[238:239], v180 offset:0x2a00
	s_waitcnt lgkmcnt(6)
	v_mfma_f32_32x32x16_bf16 v[0:15], v[228:231], v[248:251], v[0:15]
	ds_read_b64_tr_b16 v[248:249], v180 offset:0x3200
	ds_read_b64_tr_b16 v[250:251], v180 offset:0x3a00
	s_waitcnt lgkmcnt(6)
	v_mfma_f32_32x32x16_bf16 v[48:63], v[148:151], v[172:175], v[48:63]
	ds_read_b64_tr_b16 v[172:173], v180 offset:0x400
	ds_read_b64_tr_b16 v[174:175], v180 offset:0xc00
	s_waitcnt lgkmcnt(6)
	v_mfma_f32_32x32x16_bf16 v[48:63], v[220:223], v[232:235], v[48:63]
	ds_read_b64_tr_b16 v[232:233], v180 offset:0x1400
	ds_read_b64_tr_b16 v[234:235], v180 offset:0x1c00
	s_waitcnt lgkmcnt(6)
	v_mfma_f32_32x32x16_bf16 v[48:63], v[224:227], v[236:239], v[48:63]
	ds_read_b64_tr_b16 v[236:237], v180 offset:0x2400
	ds_read_b64_tr_b16 v[238:239], v180 offset:0x2c00
	s_waitcnt lgkmcnt(6)
	v_mfma_f32_32x32x16_bf16 v[48:63], v[228:231], v[248:251], v[48:63]
	ds_read_b64_tr_b16 v[248:249], v180 offset:0x3400
	ds_read_b64_tr_b16 v[250:251], v180 offset:0x3c00
	s_waitcnt lgkmcnt(6)
	v_mfma_f32_32x32x16_bf16 v[32:47], v[148:151], v[172:175], v[32:47]
	ds_read_b64_tr_b16 v[172:173], v180 offset:0x600
	ds_read_b64_tr_b16 v[174:175], v180 offset:0xe00
	s_waitcnt lgkmcnt(6)
	v_mfma_f32_32x32x16_bf16 v[32:47], v[220:223], v[232:235], v[32:47]
	ds_read_b64_tr_b16 v[232:233], v180 offset:0x1600
	ds_read_b64_tr_b16 v[234:235], v180 offset:0x1e00
	s_waitcnt lgkmcnt(6)
	v_mfma_f32_32x32x16_bf16 v[32:47], v[224:227], v[236:239], v[32:47]
	ds_read_b64_tr_b16 v[236:237], v180 offset:0x2600
	ds_read_b64_tr_b16 v[238:239], v180 offset:0x2e00
	s_waitcnt lgkmcnt(6)
	v_mfma_f32_32x32x16_bf16 v[32:47], v[228:231], v[248:251], v[32:47]
	ds_read_b64_tr_b16 v[248:249], v180 offset:0x3600
	ds_read_b64_tr_b16 v[250:251], v180 offset:0x3e00
	s_waitcnt lgkmcnt(6)
	v_mfma_f32_32x32x16_bf16 v[16:31], v[148:151], v[172:175], v[16:31]
	v_max_f32_e32 v148, v81, v81
	v_max_f32_e32 v149, v80, v80
	v_max_f32_e32 v148, v149, v148
	v_max3_f32 v148, v148, v82, v83
	v_max3_f32 v148, v148, v84, v85
	v_max3_f32 v148, v148, v86, v87
	v_max3_f32 v148, v148, v88, v89
	v_max3_f32 v148, v148, v90, v91
	v_max3_f32 v148, v148, v92, v93
	s_waitcnt lgkmcnt(4)
	v_mfma_f32_32x32x16_bf16 v[16:31], v[220:223], v[232:235], v[16:31]
	v_max3_f32 v148, v148, v94, v95
	v_max3_f32 v148, v148, v64, v65
	v_max3_f32 v148, v148, v66, v67
	v_max3_f32 v148, v148, v68, v69
	v_max3_f32 v148, v148, v70, v71
	v_max3_f32 v148, v148, v72, v73
	v_max3_f32 v148, v148, v74, v75
	v_max3_f32 v148, v148, v76, v77
	s_waitcnt lgkmcnt(2)
	v_mfma_f32_32x32x16_bf16 v[16:31], v[224:227], v[236:239], v[16:31]
	v_max3_f32 v148, v148, v78, v79
	v_mov_b32_e32 v149, v148
	s_nop 1
	v_permlane32_swap_b32_e32 v148, v149
	v_max_f32_e32 v149, v149, v149
	v_max_f32_e32 v148, v148, v148
	v_max_f32_e32 v148, v148, v149
	v_sub_f32_e32 v149, v148, v153
	v_cmp_ge_f32_e32 vcc, s90, v149
	v_max_f32_e32 v149, v153, v153
	v_max_f32_e32 v149, v149, v148
	s_waitcnt lgkmcnt(0)
	v_mfma_f32_32x32x16_bf16 v[16:31], v[228:231], v[248:251], v[16:31]
	v_sub_f32_e32 v148, v153, v149
	v_mul_f32_e32 v148, 0x3dd53b94, v148
	v_exp_f32_e32 v148, v148
	s_cmp_eq_u64 vcc, exec
	s_cselect_b64 s[6:7], -1, 0
	s_barrier
	s_waitcnt vmcnt(0)
	v_cndmask_b32_e64 v148, v148, 1.0, s[6:7]
	v_cmp_gt_f32_e32 vcc, 1.0, v148
	s_waitcnt vmcnt(4)
	ds_write_b128 v185, v[128:131] offset:16384
	s_waitcnt vmcnt(2)
	ds_write_b128 v186, v[140:143] offset:16384
	ds_write_b128 v187, v[132:135] offset:49152
	s_waitcnt vmcnt(1)
	ds_write_b128 v188, v[136:139] offset:49152
	s_waitcnt vmcnt(0)
	ds_write_b128 v208, v[144:147]
	s_cbranch_vccz .LBB0_569
	s_and_saveexec_b64 s[0:1], s[4:5]
	ds_write_b32 v178, v148 offset:128
	s_or_b64 exec, exec, s[0:1]
	s_waitcnt lgkmcnt(0)
	v_add_u32_e32 v140, v157, v160
	ds_read_b128 v[128:131], v140 offset:224
	ds_read_b128 v[132:135], v140 offset:192
	ds_read_b128 v[136:139], v140 offset:160
	ds_read_b128 v[140:143], v140 offset:128
	s_waitcnt lgkmcnt(3)
	v_pk_mul_f32 v[12:13], v[12:13], v[128:129]
	s_waitcnt lgkmcnt(2)
	v_pk_mul_f32 v[8:9], v[8:9], v[132:133]
	s_waitcnt lgkmcnt(1)
	v_pk_mul_f32 v[4:5], v[4:5], v[136:137]
	v_pk_mul_f32 v[14:15], v[14:15], v[130:131]
	v_pk_mul_f32 v[10:11], v[10:11], v[134:135]
	v_pk_mul_f32 v[6:7], v[6:7], v[138:139]
	s_waitcnt lgkmcnt(0)
	v_pk_mul_f32 v[2:3], v[2:3], v[142:143]
	v_pk_mul_f32 v[0:1], v[0:1], v[140:141]
	v_pk_mul_f32 v[60:61], v[60:61], v[128:129]
	v_pk_mul_f32 v[56:57], v[56:57], v[132:133]
	v_pk_mul_f32 v[52:53], v[52:53], v[136:137]
	v_pk_mul_f32 v[62:63], v[62:63], v[130:131]
	v_pk_mul_f32 v[58:59], v[58:59], v[134:135]
	v_pk_mul_f32 v[54:55], v[54:55], v[138:139]
	v_pk_mul_f32 v[50:51], v[50:51], v[142:143]
	v_pk_mul_f32 v[48:49], v[48:49], v[140:141]
	v_pk_mul_f32 v[44:45], v[44:45], v[128:129]
	v_pk_mul_f32 v[40:41], v[40:41], v[132:133]
	v_pk_mul_f32 v[36:37], v[36:37], v[136:137]
	v_pk_mul_f32 v[46:47], v[46:47], v[130:131]
	v_pk_mul_f32 v[42:43], v[42:43], v[134:135]
	v_pk_mul_f32 v[38:39], v[38:39], v[138:139]
	v_pk_mul_f32 v[34:35], v[34:35], v[142:143]
	v_pk_mul_f32 v[32:33], v[32:33], v[140:141]
	v_pk_mul_f32 v[28:29], v[28:29], v[128:129]
	v_pk_mul_f32 v[24:25], v[24:25], v[132:133]
	v_pk_mul_f32 v[20:21], v[20:21], v[136:137]
	v_pk_mul_f32 v[30:31], v[30:31], v[130:131]
	v_pk_mul_f32 v[26:27], v[26:27], v[134:135]
	v_pk_mul_f32 v[22:23], v[22:23], v[138:139]
	v_pk_mul_f32 v[18:19], v[18:19], v[142:143]
	v_pk_mul_f32 v[16:17], v[16:17], v[140:141]
